# baseline (speedup 1.0000x reference)
; __device__ __forceinline__ float bf2f(bf16_t b) { return __uint_as_float(((unsigned)b) << 16); }
; __device__ __forceinline__ void gla_gate(unsigned char* lds, const bf16_t* P, const float* wgu, const float* bgt, int row0, int nvalid, int h, float (&bc)[16], float& blast) {
;     ...
;     { const bf16_t* gp = P + (size_t)row0 * NPROJ + C_GL;
;       for (int idx = tid; idx < 1024; idx += 512) { const int t = idx >> 4, r = idx & 15; gl[idx] = (t < nvalid) ? bf2f(gp[t * NPROJ + r]) : 0.f; } }
.LBB0_725:
	v_mov_b32_e32 v24, v250
	s_movk_i32 s8, 0x400
	s_waitcnt lgkmcnt(0)
	v_readfirstlane_b32 s20, v24
	v_cmp_gt_i32_e32 vcc, s8, v24
	s_barrier
	s_and_saveexec_b64 s[8:9], vcc
	s_cbranch_execz .LBB0_730
	s_mul_i32 s11, s17, 0x3200
	v_readlane_b32 s12, v251, 50
	s_mul_hi_u32 s10, s17, 0x3200
	v_readlane_b32 s13, v251, 51
	s_add_u32 s11, s12, s11
	s_addc_u32 s12, s13, s10
	s_add_u32 s10, s11, 0x3000
	s_addc_u32 s11, s12, 0
	v_and_b32_e32 v25, 15, v24
	v_lshl_add_u32 v26, v24, 2, 0
	s_mov_b64 s[12:13], 0
	v_mov_b32_e32 v27, v24
	v_ashrrev_i32_e32 v246, 4, v24
	v_mul_lo_u32 v246, v246, s62
	v_or_b32_e32 v246, v246, v25
	v_ashrrev_i32_e32 v247, 31, v246
	v_lshl_add_u64 v[246:247], v[246:247], 1, s[10:11]
	global_load_ushort v248, v[246:247], off
	v_add_co_u32_e32 v246, vcc, 0x64000, v246
	s_nop 1
	v_addc_co_u32_e32 v247, vcc, 0, v247, vcc
	global_load_ushort v249, v[246:247], off
	s_branch .LBB0_728

; __device__ __forceinline__ float bf2f(bf16_t b) { return __uint_as_float(((unsigned)b) << 16); }
; __device__ __forceinline__ void gla_gate(unsigned char* lds, const bf16_t* P, const float* wgu, const float* bgt, int row0, int nvalid, int h, float (&bc)[16], float& blast) {
;     ...
;     { const bf16_t* gp = P + (size_t)row0 * NPROJ + C_GL;
;       for (int idx = tid; idx < 1024; idx += 512) { const int t = idx >> 4, r = idx & 15; gl[idx] = (t < nvalid) ? bf2f(gp[t * NPROJ + r]) : 0.f; } }
.LBB0_964:
	v_mov_b32_e32 v0, v250
	s_movk_i32 s0, 0x400
	s_waitcnt lgkmcnt(0)
	v_readfirstlane_b32 s90, v0
	v_cmp_gt_i32_e32 vcc, s0, v0
	s_barrier
	s_and_saveexec_b64 s[0:1], vcc
	s_cbranch_execz .LBB0_969
	s_mul_i32 s15, s75, 0x3200
	v_readlane_b32 s16, v251, 50
	s_mul_hi_i32 s14, s75, 0x3200
	v_readlane_b32 s17, v251, 51
	s_add_u32 s15, s16, s15
	s_addc_u32 s16, s17, s14
	s_add_u32 s14, s15, 0x3000
	s_addc_u32 s15, s16, 0
	v_and_b32_e32 v1, 15, v0
	v_lshl_add_u32 v2, v0, 2, 0
	s_mov_b64 s[16:17], 0
	v_mov_b32_e32 v3, v0
	v_ashrrev_i32_e32 v246, 4, v0
	v_mul_lo_u32 v246, v246, s26
	v_or_b32_e32 v246, v246, v1
	v_ashrrev_i32_e32 v247, 31, v246
	v_lshl_add_u64 v[246:247], v[246:247], 1, s[14:15]
	global_load_ushort v248, v[246:247], off
	v_add_co_u32_e32 v246, vcc, 0x64000, v246
	s_nop 1
	v_addc_co_u32_e32 v247, vcc, 0, v247, vcc
	global_load_ushort v249, v[246:247], off
	s_branch .LBB0_967
